# EpiFinal (last GEMM) final scaling loop: final_norm weight vectors and row statistics loaded once up front instead of 40 serialized load-wait-store round trips per tile
# baseline (speedup 1.0000x reference)
; template <int RSM> __device__ __forceinline__ float row_scale(const float* p, int row) { const float v = __hip_atomic_load(p + row, __ATOMIC_RELAXED, __HIP_MEMORY_SCOPE_AGENT); return RSM == 0 ? v : 1.0f / sqrtf(v * (1.f / DM) + EPS); }
;     __device__ __forceinline__ void operator()(f32x4 (&acc)[2][2][4][2], const Unit& u, int wr, int wc, int fr, int fq) const {
;     ...
;         for (int ai = 0; ai < 2; ++ai)
; #pragma unroll
;             for (int m = 0; m < 4; ++m) { const int row = row0 + ai * HALF + m * 16; const size_t off = (size_t)row * ldc + col0; const float rs = row_scale<1>(ss, row);
; #pragma unroll
;                 for (int bj = 0; bj < 2; ++bj)
; #pragma unroll
;                     for (int n = 0; n < 2; ++n) { const size_t p = off + bj * HALF + n * 16; const f32x4 w4 = *(const f32x4*)(wfin + col0 + bj * HALF + n * 16); *(f32x4*)(out + p) = acc[ai][bj][m][n] * rs * w4; } }
.LBB0_2086:
	s_or_b64 exec, exec, s[6:7]
	global_load_dwordx4 v[72:75], v[182:183], off
	global_load_dwordx4 v[76:79], v[182:183], off offset:64
	global_load_dwordx4 v[80:83], v[182:183], off offset:512
	global_load_dwordx4 v[84:87], v[182:183], off offset:576
	global_load_dword v88, v[112:113], off sc1
	global_load_dword v89, v[214:215], off sc1
	global_load_dword v90, v[212:213], off sc1
	global_load_dword v91, v[138:139], off sc1
	global_load_dword v92, v[112:113], off offset:512 sc1
	global_load_dword v93, v[112:113], off offset:576 sc1
	global_load_dword v94, v[112:113], off offset:640 sc1
	global_load_dword v95, v[112:113], off offset:704 sc1
	s_waitcnt vmcnt(0)
	v_mov_b32_e32 v64, v88
	s_waitcnt lgkmcnt(0)
	s_nop 0
	v_fmamk_f32 v64, v64, 0x3a000000, v230
	v_mul_f32_e32 v65, 0x4f800000, v64
	v_cmp_gt_f32_e32 vcc, s42, v64
	s_nop 1
	v_cndmask_b32_e32 v64, v64, v65, vcc
	v_sqrt_f32_e32 v65, v64
	s_nop 0
	v_add_u32_e32 v66, -1, v65
	v_add_u32_e32 v67, 1, v65
	v_fma_f32 v68, -v66, v65, v64
	v_fma_f32 v69, -v67, v65, v64
	v_cmp_ge_f32_e64 s[6:7], 0, v68
	s_nop 1
	v_cndmask_b32_e64 v65, v65, v66, s[6:7]
	v_cmp_lt_f32_e64 s[6:7], 0, v69
	s_nop 1
	v_cndmask_b32_e64 v65, v65, v67, s[6:7]
	v_mul_f32_e32 v66, 0x37800000, v65
	v_cndmask_b32_e32 v65, v65, v66, vcc
	v_cmp_class_f32_e32 vcc, v64, v231
	s_nop 1
	v_cndmask_b32_e32 v64, v65, v64, vcc
	v_div_scale_f32 v65, s[6:7], v64, v64, 1.0
	v_rcp_f32_e32 v66, v65
	v_div_scale_f32 v67, vcc, 1.0, v64, 1.0
	v_fma_f32 v68, -v65, v66, 1.0
	v_fmac_f32_e32 v66, v68, v66
	v_mul_f32_e32 v68, v67, v66
	v_fma_f32 v69, -v65, v68, v67
	v_fmac_f32_e32 v68, v69, v66
	v_fma_f32 v65, -v65, v68, v67
	v_div_fmas_f32 v65, v65, v66, v68
	v_div_fixup_f32 v64, v65, v64, 1.0
	v_pk_mul_f32 v[66:67], v[210:211], v[64:65] op_sel_hi:[1,0]
	v_pk_mul_f32 v[68:69], v[202:203], v[64:65] op_sel_hi:[1,0]
	v_pk_mul_f32 v[16:17], v[72:73], v[66:67]
	v_pk_mul_f32 v[18:19], v[74:75], v[68:69]
	global_store_dwordx4 v[194:195], v[16:19], off
	s_nop 0
	v_pk_mul_f32 v[66:67], v[200:201], v[64:65] op_sel_hi:[1,0]
	v_pk_mul_f32 v[68:69], v[208:209], v[64:65] op_sel_hi:[1,0]
	v_pk_mul_f32 v[18:19], v[78:79], v[66:67]
	v_pk_mul_f32 v[16:17], v[76:77], v[68:69]
	global_store_dwordx4 v[194:195], v[16:19], off offset:64
	s_nop 0
	v_pk_mul_f32 v[66:67], v[198:199], v[64:65] op_sel_hi:[1,0]
	v_pk_mul_f32 v[68:69], v[206:207], v[64:65] op_sel_hi:[1,0]
	v_pk_mul_f32 v[18:19], v[82:83], v[66:67]
	v_pk_mul_f32 v[16:17], v[80:81], v[68:69]
	global_store_dwordx4 v[194:195], v[16:19], off offset:512
	s_nop 0
	v_pk_mul_f32 v[66:67], v[196:197], v[64:65] op_sel_hi:[1,0]
	v_pk_mul_f32 v[64:65], v[204:205], v[64:65] op_sel_hi:[1,0]
	v_pk_mul_f32 v[18:19], v[86:87], v[66:67]
	v_pk_mul_f32 v[16:17], v[84:85], v[64:65]
	global_store_dwordx4 v[194:195], v[16:19], off offset:576
	v_mov_b32_e32 v64, v89
	s_nop 0
	s_nop 0
	v_fmamk_f32 v64, v64, 0x3a000000, v230
	v_mul_f32_e32 v65, 0x4f800000, v64
	v_cmp_gt_f32_e32 vcc, s42, v64
	s_nop 1
	v_cndmask_b32_e32 v64, v64, v65, vcc
	v_sqrt_f32_e32 v65, v64
	s_nop 0
	v_add_u32_e32 v66, -1, v65
	v_add_u32_e32 v67, 1, v65
	v_fma_f32 v68, -v66, v65, v64
	v_fma_f32 v69, -v67, v65, v64
	v_cmp_ge_f32_e64 s[6:7], 0, v68
	s_nop 1
	v_cndmask_b32_e64 v65, v65, v66, s[6:7]
	v_cmp_lt_f32_e64 s[6:7], 0, v69
	s_nop 1
	v_cndmask_b32_e64 v65, v65, v67, s[6:7]
	v_mul_f32_e32 v66, 0x37800000, v65
	v_cndmask_b32_e32 v65, v65, v66, vcc
	v_cmp_class_f32_e32 vcc, v64, v231
	s_nop 1
	v_cndmask_b32_e32 v64, v65, v64, vcc
	v_div_scale_f32 v65, s[6:7], v64, v64, 1.0
	v_rcp_f32_e32 v66, v65
	v_div_scale_f32 v67, vcc, 1.0, v64, 1.0
	v_fma_f32 v68, -v65, v66, 1.0
	v_fmac_f32_e32 v66, v68, v66
	v_mul_f32_e32 v68, v67, v66
	v_fma_f32 v69, -v65, v68, v67
	v_fmac_f32_e32 v68, v69, v66
	v_fma_f32 v65, -v65, v68, v67
	v_div_fmas_f32 v65, v65, v66, v68
	v_div_fixup_f32 v64, v65, v64, 1.0
	v_pk_mul_f32 v[66:67], v[172:173], v[64:65] op_sel_hi:[1,0]
	v_pk_mul_f32 v[68:69], v[174:175], v[64:65] op_sel_hi:[1,0]
	v_pk_mul_f32 v[16:17], v[72:73], v[66:67]
	v_pk_mul_f32 v[18:19], v[74:75], v[68:69]
	global_store_dwordx4 v[192:193], v[16:19], off
	s_nop 0
	v_pk_mul_f32 v[66:67], v[170:171], v[64:65] op_sel_hi:[1,0]
	v_pk_mul_f32 v[68:69], v[168:169], v[64:65] op_sel_hi:[1,0]
	v_pk_mul_f32 v[18:19], v[78:79], v[66:67]
	v_pk_mul_f32 v[16:17], v[76:77], v[68:69]
	global_store_dwordx4 v[192:193], v[16:19], off offset:64
	s_nop 0
	v_pk_mul_f32 v[66:67], v[166:167], v[64:65] op_sel_hi:[1,0]
	v_pk_mul_f32 v[68:69], v[164:165], v[64:65] op_sel_hi:[1,0]
	v_pk_mul_f32 v[18:19], v[82:83], v[66:67]
	v_pk_mul_f32 v[16:17], v[80:81], v[68:69]
	global_store_dwordx4 v[192:193], v[16:19], off offset:512
	s_nop 0
	v_pk_mul_f32 v[66:67], v[162:163], v[64:65] op_sel_hi:[1,0]
	v_pk_mul_f32 v[64:65], v[160:161], v[64:65] op_sel_hi:[1,0]
	v_pk_mul_f32 v[18:19], v[86:87], v[66:67]
	v_pk_mul_f32 v[16:17], v[84:85], v[64:65]
	global_store_dwordx4 v[192:193], v[16:19], off offset:576
	v_mov_b32_e32 v64, v90
	s_nop 0
	s_nop 0
	v_fmamk_f32 v64, v64, 0x3a000000, v230
	v_mul_f32_e32 v65, 0x4f800000, v64
	v_cmp_gt_f32_e32 vcc, s42, v64
	s_nop 1
	v_cndmask_b32_e32 v64, v64, v65, vcc
	v_sqrt_f32_e32 v65, v64
	s_nop 0
	v_add_u32_e32 v66, -1, v65
	v_add_u32_e32 v67, 1, v65
	v_fma_f32 v68, -v66, v65, v64
	v_fma_f32 v69, -v67, v65, v64
	v_cmp_ge_f32_e64 s[6:7], 0, v68
	s_nop 1
	v_cndmask_b32_e64 v65, v65, v66, s[6:7]
	v_cmp_lt_f32_e64 s[6:7], 0, v69
	s_nop 1
	v_cndmask_b32_e64 v65, v65, v67, s[6:7]
	v_mul_f32_e32 v66, 0x37800000, v65
	v_cndmask_b32_e32 v65, v65, v66, vcc
	v_cmp_class_f32_e32 vcc, v64, v231
	s_nop 1
	v_cndmask_b32_e32 v64, v65, v64, vcc
	v_div_scale_f32 v65, s[6:7], v64, v64, 1.0
; template <int RSM> __device__ __forceinline__ float row_scale(const float* p, int row) { const float v = __hip_atomic_load(p + row, __ATOMIC_RELAXED, __HIP_MEMORY_SCOPE_AGENT); return RSM == 0 ? v : 1.0f / sqrtf(v * (1.f / DM) + EPS); }
;     __device__ __forceinline__ void operator()(f32x4 (&acc)[2][2][4][2], const Unit& u, int wr, int wc, int fr, int fq) const {
;     ...
;         for (int ai = 0; ai < 2; ++ai)
; #pragma unroll
;             for (int m = 0; m < 4; ++m) { const int row = row0 + ai * HALF + m * 16; const size_t off = (size_t)row * ldc + col0; const float rs = row_scale<1>(ss, row);
; #pragma unroll
;                 for (int bj = 0; bj < 2; ++bj)
; #pragma unroll
;                     for (int n = 0; n < 2; ++n) { const size_t p = off + bj * HALF + n * 16; const f32x4 w4 = *(const f32x4*)(wfin + col0 + bj * HALF + n * 16); *(f32x4*)(out + p) = acc[ai][bj][m][n] * rs * w4; } }
	v_rcp_f32_e32 v66, v65
	v_div_scale_f32 v67, vcc, 1.0, v64, 1.0
	v_fma_f32 v68, -v65, v66, 1.0
	v_fmac_f32_e32 v66, v68, v66
	v_mul_f32_e32 v68, v67, v66
	v_fma_f32 v69, -v65, v68, v67
	v_fmac_f32_e32 v68, v69, v66
	v_fma_f32 v65, -v65, v68, v67
	v_div_fmas_f32 v65, v65, v66, v68
	v_div_fixup_f32 v64, v65, v64, 1.0
	v_pk_mul_f32 v[66:67], v[156:157], v[64:65] op_sel_hi:[1,0]
	v_pk_mul_f32 v[68:69], v[158:159], v[64:65] op_sel_hi:[1,0]
	v_pk_mul_f32 v[16:17], v[72:73], v[66:67]
	v_pk_mul_f32 v[18:19], v[74:75], v[68:69]
	global_store_dwordx4 v[190:191], v[16:19], off
	s_nop 0
	v_pk_mul_f32 v[66:67], v[154:155], v[64:65] op_sel_hi:[1,0]
	v_pk_mul_f32 v[68:69], v[152:153], v[64:65] op_sel_hi:[1,0]
	v_pk_mul_f32 v[18:19], v[78:79], v[66:67]
	v_pk_mul_f32 v[16:17], v[76:77], v[68:69]
	global_store_dwordx4 v[190:191], v[16:19], off offset:64
	s_nop 0
	v_pk_mul_f32 v[66:67], v[150:151], v[64:65] op_sel_hi:[1,0]
	v_pk_mul_f32 v[68:69], v[148:149], v[64:65] op_sel_hi:[1,0]
	v_pk_mul_f32 v[18:19], v[82:83], v[66:67]
	v_pk_mul_f32 v[16:17], v[80:81], v[68:69]
	global_store_dwordx4 v[190:191], v[16:19], off offset:512
	s_nop 0
	v_pk_mul_f32 v[66:67], v[146:147], v[64:65] op_sel_hi:[1,0]
	v_pk_mul_f32 v[64:65], v[144:145], v[64:65] op_sel_hi:[1,0]
	v_pk_mul_f32 v[18:19], v[86:87], v[66:67]
	v_pk_mul_f32 v[16:17], v[84:85], v[64:65]
	global_store_dwordx4 v[190:191], v[16:19], off offset:576
	v_mov_b32_e32 v64, v91
	s_nop 0
	s_nop 0
	v_fmamk_f32 v64, v64, 0x3a000000, v230
	v_mul_f32_e32 v65, 0x4f800000, v64
	v_cmp_gt_f32_e32 vcc, s42, v64
	s_nop 1
	v_cndmask_b32_e32 v64, v64, v65, vcc
	v_sqrt_f32_e32 v65, v64
	s_nop 0
	v_add_u32_e32 v66, -1, v65
	v_add_u32_e32 v67, 1, v65
	v_fma_f32 v68, -v66, v65, v64
	v_fma_f32 v69, -v67, v65, v64
	v_cmp_ge_f32_e64 s[6:7], 0, v68
	s_nop 1
	v_cndmask_b32_e64 v65, v65, v66, s[6:7]
	v_cmp_lt_f32_e64 s[6:7], 0, v69
	s_nop 1
	v_cndmask_b32_e64 v65, v65, v67, s[6:7]
	v_mul_f32_e32 v66, 0x37800000, v65
	v_cndmask_b32_e32 v65, v65, v66, vcc
	v_cmp_class_f32_e32 vcc, v64, v231
	s_nop 1
	v_cndmask_b32_e32 v64, v65, v64, vcc
	v_div_scale_f32 v65, s[6:7], v64, v64, 1.0
	v_rcp_f32_e32 v66, v65
	v_div_scale_f32 v67, vcc, 1.0, v64, 1.0
	v_fma_f32 v68, -v65, v66, 1.0
	v_fmac_f32_e32 v66, v68, v66
	v_mul_f32_e32 v68, v67, v66
	v_fma_f32 v69, -v65, v68, v67
	v_fmac_f32_e32 v68, v69, v66
	v_fma_f32 v65, -v65, v68, v67
	v_div_fmas_f32 v65, v65, v66, v68
	v_div_fixup_f32 v64, v65, v64, 1.0
	v_pk_mul_f32 v[66:67], v[140:141], v[64:65] op_sel_hi:[1,0]
	v_pk_mul_f32 v[68:69], v[142:143], v[64:65] op_sel_hi:[1,0]
	v_pk_mul_f32 v[16:17], v[72:73], v[66:67]
	v_pk_mul_f32 v[18:19], v[74:75], v[68:69]
	global_store_dwordx4 v[188:189], v[16:19], off
	s_nop 0
	v_pk_mul_f32 v[66:67], v[126:127], v[64:65] op_sel_hi:[1,0]
	v_pk_mul_f32 v[68:69], v[136:137], v[64:65] op_sel_hi:[1,0]
	v_pk_mul_f32 v[18:19], v[78:79], v[66:67]
	v_pk_mul_f32 v[16:17], v[76:77], v[68:69]
	global_store_dwordx4 v[188:189], v[16:19], off offset:64
	s_nop 0
	v_pk_mul_f32 v[66:67], v[124:125], v[64:65] op_sel_hi:[1,0]
	v_pk_mul_f32 v[68:69], v[132:133], v[64:65] op_sel_hi:[1,0]
	v_pk_mul_f32 v[18:19], v[82:83], v[66:67]
	v_pk_mul_f32 v[16:17], v[80:81], v[68:69]
	global_store_dwordx4 v[188:189], v[16:19], off offset:512
	s_nop 0
	v_pk_mul_f32 v[66:67], v[122:123], v[64:65] op_sel_hi:[1,0]
	v_pk_mul_f32 v[64:65], v[128:129], v[64:65] op_sel_hi:[1,0]
	v_pk_mul_f32 v[18:19], v[86:87], v[66:67]
	v_pk_mul_f32 v[16:17], v[84:85], v[64:65]
	global_store_dwordx4 v[188:189], v[16:19], off offset:576
	v_mov_b32_e32 v64, v92
	s_nop 0
	s_nop 0
	v_fmamk_f32 v64, v64, 0x3a000000, v230
	v_mul_f32_e32 v65, 0x4f800000, v64
	v_cmp_gt_f32_e32 vcc, s42, v64
	s_nop 1
	v_cndmask_b32_e32 v64, v64, v65, vcc
	v_sqrt_f32_e32 v65, v64
	s_nop 0
	v_add_u32_e32 v66, -1, v65
	v_add_u32_e32 v67, 1, v65
	v_fma_f32 v68, -v66, v65, v64
	v_fma_f32 v69, -v67, v65, v64
	v_cmp_ge_f32_e64 s[6:7], 0, v68
	s_nop 1
	v_cndmask_b32_e64 v65, v65, v66, s[6:7]
	v_cmp_lt_f32_e64 s[6:7], 0, v69
	s_nop 1
	v_cndmask_b32_e64 v65, v65, v67, s[6:7]
	v_mul_f32_e32 v66, 0x37800000, v65
	v_cndmask_b32_e32 v65, v65, v66, vcc
	v_cmp_class_f32_e32 vcc, v64, v231
	s_nop 1
	v_cndmask_b32_e32 v64, v65, v64, vcc
	v_div_scale_f32 v65, s[6:7], v64, v64, 1.0
	v_rcp_f32_e32 v66, v65
	v_div_scale_f32 v67, vcc, 1.0, v64, 1.0
	v_fma_f32 v68, -v65, v66, 1.0
	v_fmac_f32_e32 v66, v68, v66
	v_mul_f32_e32 v68, v67, v66
	v_fma_f32 v69, -v65, v68, v67
	v_fmac_f32_e32 v68, v69, v66
	v_fma_f32 v65, -v65, v68, v67
	v_div_fmas_f32 v65, v65, v66, v68
	v_div_fixup_f32 v64, v65, v64, 1.0
	v_pk_mul_f32 v[66:67], v[134:135], v[64:65] op_sel_hi:[1,0]
	v_pk_mul_f32 v[62:63], v[62:63], v[64:65] op_sel_hi:[1,0]
	v_pk_mul_f32 v[16:17], v[72:73], v[66:67]
	v_pk_mul_f32 v[18:19], v[74:75], v[62:63]
	global_store_dwordx4 v[120:121], v[16:19], off
	s_nop 0
	v_pk_mul_f32 v[58:59], v[58:59], v[64:65] op_sel_hi:[1,0]
	v_pk_mul_f32 v[62:63], v[130:131], v[64:65] op_sel_hi:[1,0]
	v_pk_mul_f32 v[54:55], v[54:55], v[64:65] op_sel_hi:[1,0]
	v_pk_mul_f32 v[52:53], v[52:53], v[64:65] op_sel_hi:[1,0]
	v_pk_mul_f32 v[16:17], v[76:77], v[62:63]
	v_pk_mul_f32 v[18:19], v[78:79], v[58:59]
	global_store_dwordx4 v[120:121], v[16:19], off offset:64
	s_nop 0
	v_pk_mul_f32 v[58:59], v[60:61], v[64:65] op_sel_hi:[1,0]
	v_pk_mul_f32 v[18:19], v[82:83], v[54:55]
	v_pk_mul_f32 v[16:17], v[80:81], v[58:59]
	global_store_dwordx4 v[120:121], v[16:19], off offset:512
	s_nop 0
	v_pk_mul_f32 v[54:55], v[56:57], v[64:65] op_sel_hi:[1,0]
	v_pk_mul_f32 v[18:19], v[86:87], v[52:53]
	v_pk_mul_f32 v[16:17], v[84:85], v[54:55]
	global_store_dwordx4 v[120:121], v[16:19], off offset:576
	v_mov_b32_e32 v52, v93
; template <int RSM> __device__ __forceinline__ float row_scale(const float* p, int row) { const float v = __hip_atomic_load(p + row, __ATOMIC_RELAXED, __HIP_MEMORY_SCOPE_AGENT); return RSM == 0 ? v : 1.0f / sqrtf(v * (1.f / DM) + EPS); }
;     __device__ __forceinline__ void operator()(f32x4 (&acc)[2][2][4][2], const Unit& u, int wr, int wc, int fr, int fq) const {
;     ...
;         for (int ai = 0; ai < 2; ++ai)
; #pragma unroll
;             for (int m = 0; m < 4; ++m) { const int row = row0 + ai * HALF + m * 16; const size_t off = (size_t)row * ldc + col0; const float rs = row_scale<1>(ss, row);
; #pragma unroll
;                 for (int bj = 0; bj < 2; ++bj)
; #pragma unroll
;                     for (int n = 0; n < 2; ++n) { const size_t p = off + bj * HALF + n * 16; const f32x4 w4 = *(const f32x4*)(wfin + col0 + bj * HALF + n * 16); *(f32x4*)(out + p) = acc[ai][bj][m][n] * rs * w4; } }
	s_nop 0
	s_nop 0
	v_fmamk_f32 v52, v52, 0x3a000000, v230
	v_mul_f32_e32 v53, 0x4f800000, v52
	v_cmp_gt_f32_e32 vcc, s42, v52
	s_nop 1
	v_cndmask_b32_e32 v52, v52, v53, vcc
	v_sqrt_f32_e32 v53, v52
	s_nop 0
	v_add_u32_e32 v54, -1, v53
	v_add_u32_e32 v55, 1, v53
	v_fma_f32 v56, -v54, v53, v52
	v_fma_f32 v57, -v55, v53, v52
	v_cmp_ge_f32_e64 s[6:7], 0, v56
	s_nop 1
	v_cndmask_b32_e64 v53, v53, v54, s[6:7]
	v_cmp_lt_f32_e64 s[6:7], 0, v57
	s_nop 1
	v_cndmask_b32_e64 v53, v53, v55, s[6:7]
	v_mul_f32_e32 v54, 0x37800000, v53
	v_cndmask_b32_e32 v53, v53, v54, vcc
	v_cmp_class_f32_e32 vcc, v52, v231
	s_nop 1
	v_cndmask_b32_e32 v52, v53, v52, vcc
	v_div_scale_f32 v53, s[6:7], v52, v52, 1.0
	v_rcp_f32_e32 v54, v53
	v_div_scale_f32 v55, vcc, 1.0, v52, 1.0
	v_fma_f32 v56, -v53, v54, 1.0
	v_fmac_f32_e32 v54, v56, v54
	v_mul_f32_e32 v56, v55, v54
	v_fma_f32 v57, -v53, v56, v55
	v_fmac_f32_e32 v56, v57, v54
	v_fma_f32 v53, -v53, v56, v55
	v_div_fmas_f32 v53, v53, v54, v56
	v_div_fixup_f32 v52, v53, v52, 1.0
	v_pk_mul_f32 v[50:51], v[50:51], v[52:53] op_sel_hi:[1,0]
	v_pk_mul_f32 v[46:47], v[46:47], v[52:53] op_sel_hi:[1,0]
	v_pk_mul_f32 v[16:17], v[72:73], v[50:51]
	v_pk_mul_f32 v[18:19], v[74:75], v[46:47]
	global_store_dwordx4 v[118:119], v[16:19], off
	s_nop 0
	v_pk_mul_f32 v[42:43], v[42:43], v[52:53] op_sel_hi:[1,0]
	v_pk_mul_f32 v[46:47], v[48:49], v[52:53] op_sel_hi:[1,0]
	v_pk_mul_f32 v[38:39], v[38:39], v[52:53] op_sel_hi:[1,0]
	v_pk_mul_f32 v[36:37], v[36:37], v[52:53] op_sel_hi:[1,0]
	v_pk_mul_f32 v[16:17], v[76:77], v[46:47]
	v_pk_mul_f32 v[18:19], v[78:79], v[42:43]
	global_store_dwordx4 v[118:119], v[16:19], off offset:64
	s_nop 0
	v_pk_mul_f32 v[42:43], v[44:45], v[52:53] op_sel_hi:[1,0]
	v_pk_mul_f32 v[18:19], v[82:83], v[38:39]
	v_pk_mul_f32 v[16:17], v[80:81], v[42:43]
	global_store_dwordx4 v[118:119], v[16:19], off offset:512
	s_nop 0
	v_pk_mul_f32 v[38:39], v[40:41], v[52:53] op_sel_hi:[1,0]
	v_pk_mul_f32 v[18:19], v[86:87], v[36:37]
	v_pk_mul_f32 v[16:17], v[84:85], v[38:39]
	global_store_dwordx4 v[118:119], v[16:19], off offset:576
	v_mov_b32_e32 v36, v94
	s_nop 0
	s_nop 0
	v_fmamk_f32 v36, v36, 0x3a000000, v230
	v_mul_f32_e32 v37, 0x4f800000, v36
	v_cmp_gt_f32_e32 vcc, s42, v36
	s_nop 1
	v_cndmask_b32_e32 v36, v36, v37, vcc
	v_sqrt_f32_e32 v37, v36
	s_nop 0
	v_add_u32_e32 v38, -1, v37
	v_add_u32_e32 v39, 1, v37
	v_fma_f32 v40, -v38, v37, v36
	v_fma_f32 v41, -v39, v37, v36
	v_cmp_ge_f32_e64 s[6:7], 0, v40
	s_nop 1
	v_cndmask_b32_e64 v37, v37, v38, s[6:7]
	v_cmp_lt_f32_e64 s[6:7], 0, v41
	s_nop 1
	v_cndmask_b32_e64 v37, v37, v39, s[6:7]
	v_mul_f32_e32 v38, 0x37800000, v37
	v_cndmask_b32_e32 v37, v37, v38, vcc
	v_cmp_class_f32_e32 vcc, v36, v231
	s_nop 1
	v_cndmask_b32_e32 v36, v37, v36, vcc
	v_div_scale_f32 v37, s[6:7], v36, v36, 1.0
	v_rcp_f32_e32 v38, v37
	v_div_scale_f32 v39, vcc, 1.0, v36, 1.0
	v_fma_f32 v40, -v37, v38, 1.0
	v_fmac_f32_e32 v38, v40, v38
	v_mul_f32_e32 v40, v39, v38
	v_fma_f32 v41, -v37, v40, v39
	v_fmac_f32_e32 v40, v41, v38
	v_fma_f32 v37, -v37, v40, v39
	v_div_fmas_f32 v37, v37, v38, v40
	v_div_fixup_f32 v36, v37, v36, 1.0
	v_pk_mul_f32 v[34:35], v[34:35], v[36:37] op_sel_hi:[1,0]
	v_pk_mul_f32 v[28:29], v[28:29], v[36:37] op_sel_hi:[1,0]
	v_pk_mul_f32 v[16:17], v[72:73], v[34:35]
	v_pk_mul_f32 v[18:19], v[74:75], v[28:29]
	global_store_dwordx4 v[116:117], v[16:19], off
	s_nop 0
	v_pk_mul_f32 v[26:27], v[26:27], v[36:37] op_sel_hi:[1,0]
	v_pk_mul_f32 v[28:29], v[32:33], v[36:37] op_sel_hi:[1,0]
	v_pk_mul_f32 v[22:23], v[22:23], v[36:37] op_sel_hi:[1,0]
	v_pk_mul_f32 v[20:21], v[20:21], v[36:37] op_sel_hi:[1,0]
	v_pk_mul_f32 v[16:17], v[76:77], v[28:29]
	v_pk_mul_f32 v[18:19], v[78:79], v[26:27]
	global_store_dwordx4 v[116:117], v[16:19], off offset:64
	s_nop 0
	v_pk_mul_f32 v[26:27], v[30:31], v[36:37] op_sel_hi:[1,0]
	v_pk_mul_f32 v[18:19], v[82:83], v[22:23]
	v_pk_mul_f32 v[16:17], v[80:81], v[26:27]
	global_store_dwordx4 v[116:117], v[16:19], off offset:512
	s_nop 0
	v_pk_mul_f32 v[22:23], v[24:25], v[36:37] op_sel_hi:[1,0]
	v_pk_mul_f32 v[18:19], v[86:87], v[20:21]
	v_pk_mul_f32 v[16:17], v[84:85], v[22:23]
	global_store_dwordx4 v[116:117], v[16:19], off offset:576
	v_mov_b32_e32 v20, v95
	s_nop 0
	s_nop 0
	v_fmamk_f32 v20, v20, 0x3a000000, v230
	v_mul_f32_e32 v21, 0x4f800000, v20
	v_cmp_gt_f32_e32 vcc, s42, v20
	s_nop 1
	v_cndmask_b32_e32 v20, v20, v21, vcc
	v_sqrt_f32_e32 v21, v20
	s_nop 0
	v_add_u32_e32 v22, -1, v21
	v_add_u32_e32 v23, 1, v21
	v_fma_f32 v24, -v22, v21, v20
	v_fma_f32 v25, -v23, v21, v20
	v_cmp_ge_f32_e64 s[6:7], 0, v24
	s_nop 1
	v_cndmask_b32_e64 v21, v21, v22, s[6:7]
	v_cmp_lt_f32_e64 s[6:7], 0, v25
	s_nop 1
	v_cndmask_b32_e64 v21, v21, v23, s[6:7]
	v_mul_f32_e32 v22, 0x37800000, v21
	v_cndmask_b32_e32 v21, v21, v22, vcc
	v_cmp_class_f32_e32 vcc, v20, v231
	s_nop 1
	v_cndmask_b32_e32 v20, v21, v20, vcc
	v_div_scale_f32 v21, s[6:7], v20, v20, 1.0
	v_rcp_f32_e32 v22, v21
	v_div_scale_f32 v23, vcc, 1.0, v20, 1.0
	v_fma_f32 v24, -v21, v22, 1.0
	v_fmac_f32_e32 v22, v24, v22
	v_mul_f32_e32 v24, v23, v22
	v_fma_f32 v25, -v21, v24, v23
	v_fmac_f32_e32 v24, v25, v22
	v_fma_f32 v21, -v21, v24, v23
	v_div_fmas_f32 v21, v21, v22, v24
	v_div_fixup_f32 v20, v21, v20, 1.0
	v_pk_mul_f32 v[22:23], v[14:15], v[20:21] op_sel_hi:[1,0]
	v_pk_mul_f32 v[12:13], v[12:13], v[20:21] op_sel_hi:[1,0]
	v_pk_mul_f32 v[10:11], v[10:11], v[20:21] op_sel_hi:[1,0]
	v_pk_mul_f32 v[14:15], v[74:75], v[12:13]
	v_pk_mul_f32 v[12:13], v[72:73], v[22:23]
	global_store_dwordx4 v[114:115], v[12:15], off
	s_nop 0
	v_pk_mul_f32 v[8:9], v[8:9], v[20:21] op_sel_hi:[1,0]
	v_pk_mul_f32 v[6:7], v[6:7], v[20:21] op_sel_hi:[1,0]
	v_pk_mul_f32 v[4:5], v[4:5], v[20:21] op_sel_hi:[1,0]
	v_pk_mul_f32 v[2:3], v[2:3], v[20:21] op_sel_hi:[1,0]
	v_pk_mul_f32 v[0:1], v[0:1], v[20:21] op_sel_hi:[1,0]
	s_and_b64 vcc, exec, s[4:5]
	s_mov_b64 s[4:5], -1
	v_pk_mul_f32 v[8:9], v[76:77], v[8:9]
	v_pk_mul_f32 v[10:11], v[78:79], v[10:11]
	global_store_dwordx4 v[114:115], v[8:11], off offset:64
	s_nop 0
	v_pk_mul_f32 v[4:5], v[80:81], v[4:5]
	v_pk_mul_f32 v[6:7], v[82:83], v[6:7]
	global_store_dwordx4 v[114:115], v[4:7], off offset:512
	s_nop 0
	v_pk_mul_f32 v[0:1], v[84:85], v[0:1]
	v_pk_mul_f32 v[2:3], v[86:87], v[2:3]
	global_store_dwordx4 v[114:115], v[0:3], off offset:576
	s_cbranch_vccnz .LBB0_2049
	s_andn2_b64 vcc, exec, s[10:11]
	s_cbranch_vccnz .LBB0_2048
	s_barrier
	s_branch .LBB0_2048
